# vE plus one static s_setprio 1 for waves 4-7 during the attention phase (reset to 0 at phase end); alignment of attention and GEMM loops unchanged
# speedup vs baseline: 1.0018x; 1.0018x over previous
; __device__ __forceinline__ unsigned cvt_pk_bf16(float lo, float hi) { unsigned r; asm volatile("v_cvt_pk_bf16_f32 %0, %1, %2" : "=v"(r) : "v"(lo), "v"(hi)); return r; }
; __global__ void __launch_bounds__(NTHREADS, 2) fwd_kernel(Args a) {
;     ...
;         for (int row = gw; row < S; row += NGW) {
;             const f32x4* xr = (const f32x4*)(x_in + (size_t)row * D) + lane0;
;             u32x2* o8 = (u32x2*)(xb + (size_t)row * D) + lane0;
;             float s = 0.f;
; #pragma unroll
;             for (int j = 0; j < 8; ++j) { const f32x4 v = xr[64 * j]; s += (v[0] * v[0] + v[1] * v[1]) + (v[2] * v[2] + v[3] * v[3]); u32x2 w; w.x = cvt_pk_bf16(v[0], v[1]); w.y = cvt_pk_bf16(v[2], v[3]); o8[64 * j] = w; }
;             s = wave_sum(s, lane0);
;             if (lane0 < 32) ssq1[(size_t)row * 32 + lane0] = (lane0 == 0) ? s : 0.f;
.LBB0_46:
	s_andn2_b64 vcc, exec, s[4:5]
	s_cbranch_vccnz .LBB0_25
	v_add_u32_e32 v6, 48, v21
	v_and_or_b32 v6, v6, s28, v27
	s_branch .LBB0_25
	s_nop 0
	s_nop 0
	s_nop 0
	s_nop 0
	s_nop 0
	s_nop 0
	s_nop 0
	s_nop 0
	s_nop 0
	s_nop 0
	s_nop 0
	s_nop 0
	s_nop 0
	s_nop 0
.LBB0_48:
	s_load_dword s23, s[0:1], 0xa0
	s_cmpk_gt_i32 s22, 0x1fff
	s_cbranch_scc1 .LBB0_53
	s_ashr_i32 s14, s13, 31
	v_readlane_b32 s15, v238, 20
	s_add_u32 s18, s15, s13
	s_addc_u32 s19, 0, s14
	s_load_dwordx16 s[52:67], s[0:1], 0x0
	s_lshl_b64 s[14:15], s[18:19], 7
	s_add_u32 s14, s82, s14
	v_lshlrev_b32_e32 v6, 2, v1
	v_mov_b32_e32 v7, 0
	s_addc_u32 s15, s83, s15
	s_ashr_i32 s13, s12, 31
	v_lshl_add_u64 v[2:3], s[14:15], 0, v[6:7]
	s_lshl_b64 s[14:15], s[12:13], 7
	s_lshl_b64 s[16:17], s[18:19], 13
	s_waitcnt lgkmcnt(0)
	s_add_u32 s16, s52, s16
	v_xor_b32_e32 v8, 4, v6
	v_xor_b32_e32 v9, 8, v6
	v_xor_b32_e32 v10, 16, v6
	v_xor_b32_e32 v11, 32, v6
	v_xor_b32_e32 v12, 64, v6
	v_xor_b32_e32 v13, 0x80, v6
	v_lshlrev_b32_e32 v6, 4, v1
	s_addc_u32 s17, s53, s17
	v_lshl_add_u64 v[4:5], s[16:17], 0, v[6:7]
	s_mov_b64 s[16:17], 0x1c00
	v_lshl_add_u64 v[4:5], v[4:5], 0, s[16:17]
	s_lshl_b64 s[16:17], s[12:13], 13
	s_lshl_b64 s[18:19], s[18:19], 12
	s_add_u32 s18, s82, s18
	v_lshlrev_b32_e32 v6, 3, v1
	s_addc_u32 s19, s83, s19
	v_lshl_add_u64 v[6:7], s[18:19], 0, v[6:7]
	s_mov_b64 s[18:19], 0x17100800
	v_cmp_gt_u32_e64 s[6:7], 32, v1
	v_cmp_eq_u32_e64 s[4:5], 0, v1
	v_lshl_add_u64 v[6:7], v[6:7], 0, s[18:19]
	s_lshl_b64 s[18:19], s[12:13], 12
	s_branch .LBB0_51

; #define LAS __attribute__((address_space(3)))
; __global__ void __launch_bounds__(NTHREADS, 2) fwd_kernel(Args a) {
;     ...
;             LAS float* rpl = (LAS float*)(lds + 4096 + wave * 4096 + 256);
;             const int ql = lane & 31, hi = lane >> 5, w = wave;
;             {
;                 const float* rp = rpb + ((size_t)layer * 8 + w) * (15 * 31);
;                 for (int i = lane; i < 15 * 31; i += 64) rpl[i] = rp[i] * LOG2E;
;                 asm volatile("s_waitcnt lgkmcnt(0)" ::: "memory");
.LBB0_133:
	s_cmp_gt_i32 s16, 0
	s_mov_b64 s[10:11], -1
	s_cbranch_scc0 .LBB0_168
	v_readlane_b32 s60, v238, 0
	s_lshl_b32 s14, s50, 3
	v_readlane_b32 s8, v238, 20
	v_readlane_b32 s64, v238, 4
	v_readlane_b32 s65, v238, 5
	s_add_i32 s14, s14, s8
	s_cmp_ge_u32 s8, 4
	s_cbranch_scc0 .Lattn_prio_done
	s_setprio 1
.Lattn_prio_done:
	s_nop 0
	v_readlane_b32 s66, v238, 6
	v_readlane_b32 s67, v238, 7
	v_readlane_b32 s68, v238, 8
	v_readlane_b32 s69, v238, 9
	v_readlane_b32 s70, v238, 10
	v_readlane_b32 s71, v238, 11
	v_readlane_b32 s72, v238, 12
	v_readlane_b32 s73, v238, 13
	v_readlane_b32 s74, v238, 14
	v_readlane_b32 s75, v238, 15
	s_mov_b64 s[20:21], s[64:65]
	s_mul_i32 s10, s14, 0x744
	s_mov_b64 s[28:29], s[72:73]
	v_and_b32_e32 v193, 63, v206
	s_mul_hi_u32 s11, s14, 0x744
	s_add_u32 s10, s28, s10
	s_addc_u32 s11, s29, s11
	v_lshlrev_b32_e32 v0, 2, v193
	global_load_dword v2, v0, s[10:11]
	global_load_dword v4, v0, s[10:11] offset:256
	global_load_dword v226, v0, s[10:11] offset:512
	global_load_dword v227, v0, s[10:11] offset:768
	global_load_dword v228, v0, s[10:11] offset:1024
	global_load_dword v229, v0, s[10:11] offset:1280
	global_load_dword v230, v0, s[10:11] offset:1536
	s_movk_i32 s12, 0x191
	v_readlane_b32 s61, v238, 1
	v_readlane_b32 s62, v238, 2
	v_readlane_b32 s63, v238, 3
	s_mov_b64 s[22:23], s[66:67]
	s_mov_b64 s[24:25], s[68:69]
	s_mov_b64 s[26:27], s[70:71]
	s_mov_b64 s[30:31], s[74:75]
	v_or_b32_e32 v3, 0x180, v193
	v_cmp_gt_u32_e32 vcc, s12, v3
	s_and_saveexec_b64 s[12:13], vcc
	global_load_dword v231, v0, s[10:11] offset:1792
	s_or_b64 exec, exec, s[12:13]
	s_waitcnt vmcnt(0)
	v_mul_f32_e32 v3, 0x3fb8aa3b, v2
	v_add_u32_e32 v2, s33, v0
	v_mul_f32_e32 v4, 0x3fb8aa3b, v4
	ds_write2st64_b32 v2, v3, v4 offset0:17 offset1:18
	v_mul_f32_e32 v226, 0x3fb8aa3b, v226
	v_mul_f32_e32 v227, 0x3fb8aa3b, v227
	ds_write2st64_b32 v2, v226, v227 offset0:19 offset1:20
	v_mul_f32_e32 v228, 0x3fb8aa3b, v228
	v_mul_f32_e32 v229, 0x3fb8aa3b, v229
	ds_write2st64_b32 v2, v228, v229 offset0:21 offset1:22
	v_mul_f32_e32 v230, 0x3fb8aa3b, v230
	ds_write_b32 v2, v230 offset:5888
	s_and_saveexec_b64 s[12:13], vcc
	s_cbranch_execz .LBB0_136
	v_mul_f32_e32 v231, 0x3fb8aa3b, v231
	ds_write_b32 v2, v231 offset:6144

; __global__ void __launch_bounds__(NTHREADS, 2) fwd_kernel(Args a) {
;     ...
;             for (int u0 = bid; u0 < 512; u0 += G, ++ucount) {
.LBB0_167:
	s_setprio 0
	s_nop 0
	s_nop 0
	s_nop 0
	s_nop 0
	s_nop 0
	s_nop 0
	s_nop 0
	s_nop 0
	s_nop 0
	s_nop 0
	s_nop 0
	s_nop 0
	s_nop 0
	s_nop 0
	s_nop 0
	s_mov_b64 s[10:11], 0
